# barrier spin loops poll without s_sleep
# baseline (speedup 1.0000x reference)
; __global__ void __launch_bounds__(512, 2) mega_fwd(Params prm) {
;     ...
;     grid.sync();
.LBB0_15:
	global_load_dword v2, v0, s[2:3] offset:32 sc1
	s_waitcnt vmcnt(0)
	v_and_b32_e32 v2, 0xffff0000, v2
	v_cmp_ne_u32_e32 vcc, v2, v1
	s_or_b64 s[6:7], vcc, s[6:7]
	s_andn2_b64 exec, exec, s[6:7]
	s_cbranch_execnz .LBB0_15

; __device__ __forceinline__ unsigned xb_ld(unsigned* p)              { return __hip_atomic_load(p, __ATOMIC_RELAXED, __HIP_MEMORY_SCOPE_AGENT); }
; __device__ __forceinline__ void xcd_barrier_complete(unsigned* bar, unsigned x, unsigned& nloc, unsigned& nx) {
;     const unsigned G = gridDim.x * gridDim.y * gridDim.z;
;     unsigned sum, cnt, mine, sp = 0u;
;     for (;;) {
;         sum = 0u; cnt = 0u; mine = 0u;
; #pragma unroll
;         for (unsigned j = 0; j < 16; ++j) { const unsigned c = xb_ld(&bar[XB_XCNT(j)]); sum += c; cnt += (c > 0u) ? 1u : 0u; mine = (j == x) ? c : mine; }
;         if (sum == G) break;
;         __builtin_amdgcn_s_sleep(1);
;         if ((++sp & 255u) == 0u) { if (xb_ld(&bar[XB_TMO])) break; if (sp > XB_SPIN_CAP) { atomicAdd(&bar[XB_TMO], 1u); break; } }
;     }
.LBB0_221:
	v_readlane_b32 s4, v242, 31
	v_readlane_b32 s5, v242, 32
	global_load_dword v1, v129, s[82:83] sc1
	s_waitcnt lgkmcnt(0)
	global_load_dword v0, v129, s[46:47] sc1
	s_mov_b64 s[6:7], -1
	s_waitcnt vmcnt(0)
	v_add_u32_e32 v16, v0, v1
	global_load_dword v2, v129, s[4:5] sc1
	v_readlane_b32 s4, v242, 33
	v_readlane_b32 s5, v242, 34
	s_waitcnt vmcnt(0)
	v_add_u32_e32 v16, v16, v2
	s_nop 2
	global_load_dword v3, v129, s[4:5] sc1
	v_readlane_b32 s4, v243, 0
	v_readlane_b32 s5, v243, 1
	s_waitcnt vmcnt(0)
	v_add_u32_e32 v16, v16, v3
	s_nop 2
	global_load_dword v4, v129, s[4:5] sc1
	v_readlane_b32 s4, v243, 2
	v_readlane_b32 s5, v243, 3
	s_waitcnt vmcnt(0)
	v_add_u32_e32 v16, v16, v4
	s_nop 2
	global_load_dword v5, v129, s[4:5] sc1
	v_readlane_b32 s4, v243, 4
	v_readlane_b32 s5, v243, 5
	s_waitcnt vmcnt(0)
	v_add_u32_e32 v16, v16, v5
	s_nop 2
	global_load_dword v6, v129, s[4:5] sc1
	v_readlane_b32 s4, v243, 6
	v_readlane_b32 s5, v243, 7
	s_waitcnt vmcnt(0)
	v_add_u32_e32 v16, v16, v6
	s_nop 2
	global_load_dword v7, v129, s[4:5] sc1
	v_readlane_b32 s4, v243, 8
	v_readlane_b32 s5, v243, 9
	s_waitcnt vmcnt(0)
	v_add_u32_e32 v16, v16, v7
	s_nop 2
	global_load_dword v8, v129, s[4:5] sc1
	v_readlane_b32 s4, v243, 10
	v_readlane_b32 s5, v243, 11
	s_waitcnt vmcnt(0)
	v_add_u32_e32 v16, v16, v8
	s_nop 2
	global_load_dword v9, v129, s[4:5] sc1
	v_readlane_b32 s4, v243, 12
	v_readlane_b32 s5, v243, 13
	s_waitcnt vmcnt(0)
	v_add_u32_e32 v16, v16, v9
	s_nop 2
	global_load_dword v10, v129, s[4:5] sc1
	v_readlane_b32 s4, v243, 14
	v_readlane_b32 s5, v243, 15
	s_waitcnt vmcnt(0)
	v_add_u32_e32 v16, v16, v10
	s_nop 2
	global_load_dword v11, v129, s[4:5] sc1
	v_readlane_b32 s4, v243, 16
	v_readlane_b32 s5, v243, 17
	s_waitcnt vmcnt(0)
	v_add_u32_e32 v16, v16, v11
	s_nop 2
	global_load_dword v12, v129, s[4:5] sc1
	v_readlane_b32 s4, v243, 18
	v_readlane_b32 s5, v243, 19
	s_waitcnt vmcnt(0)
	v_add_u32_e32 v16, v16, v12
	s_nop 2
	global_load_dword v13, v129, s[4:5] sc1
	v_readlane_b32 s4, v243, 20
	v_readlane_b32 s5, v243, 21
	s_waitcnt vmcnt(0)
	v_add_u32_e32 v16, v16, v13
	s_nop 2
	global_load_dword v14, v129, s[4:5] sc1
	v_readlane_b32 s4, v243, 22
	v_readlane_b32 s5, v243, 23
	s_waitcnt vmcnt(0)
	v_add_u32_e32 v16, v16, v14
	s_nop 2
	global_load_dword v15, v129, s[4:5] sc1
	s_mov_b64 s[4:5], -1
	s_waitcnt vmcnt(0)
	v_add_u32_e32 v16, v16, v15
	v_cmp_eq_u32_e32 vcc, s73, v16
	s_cbranch_vccnz .LBB0_220
	s_and_b32 s4, s10, 0xff
	s_cmp_eq_u32 s4, 0
	s_mov_b64 s[4:5], -1
	s_mov_b64 s[12:13], -1
	s_cbranch_scc1 .LBB0_225
	s_and_b64 vcc, exec, s[12:13]
	s_cbranch_vccz .LBB0_220

.LBB0_239:
	s_and_b32 s14, s10, 0xff
	s_mov_b64 s[22:23], -1
	s_cmp_lg_u32 s14, 0
	s_mov_b64 s[26:27], -1
	s_cbranch_scc0 .LBB0_242
	s_and_b64 vcc, exec, s[26:27]
	s_cbranch_vccz .LBB0_238

; __device__ __forceinline__ unsigned xb_ld(unsigned* p)              { return __hip_atomic_load(p, __ATOMIC_RELAXED, __HIP_MEMORY_SCOPE_AGENT); }
; __device__ __forceinline__ void xcd_barrier_complete(unsigned* bar, unsigned x, unsigned& nloc, unsigned& nx) {
;     const unsigned G = gridDim.x * gridDim.y * gridDim.z;
;     unsigned sum, cnt, mine, sp = 0u;
;     for (;;) {
;         sum = 0u; cnt = 0u; mine = 0u;
; #pragma unroll
;         for (unsigned j = 0; j < 16; ++j) { const unsigned c = xb_ld(&bar[XB_XCNT(j)]); sum += c; cnt += (c > 0u) ? 1u : 0u; mine = (j == x) ? c : mine; }
;         if (sum == G) break;
;         __builtin_amdgcn_s_sleep(1);
;         if ((++sp & 255u) == 0u) { if (xb_ld(&bar[XB_TMO])) break; if (sp > XB_SPIN_CAP) { atomicAdd(&bar[XB_TMO], 1u); break; } }
;     }
.LBB0_382:
	v_readlane_b32 s6, v242, 31
	v_readlane_b32 s7, v242, 32
	global_load_dword v1, v129, s[82:83] sc1
	s_waitcnt lgkmcnt(0)
	global_load_dword v0, v129, s[46:47] sc1
	s_mov_b64 s[12:13], -1
	s_waitcnt vmcnt(0)
	v_add_u32_e32 v16, v0, v1
	global_load_dword v2, v129, s[6:7] sc1
	v_readlane_b32 s6, v242, 33
	v_readlane_b32 s7, v242, 34
	s_waitcnt vmcnt(0)
	v_add_u32_e32 v16, v16, v2
	s_nop 2
	global_load_dword v3, v129, s[6:7] sc1
	v_readlane_b32 s6, v243, 0
	v_readlane_b32 s7, v243, 1
	s_waitcnt vmcnt(0)
	v_add_u32_e32 v16, v16, v3
	s_nop 2
	global_load_dword v4, v129, s[6:7] sc1
	v_readlane_b32 s6, v243, 2
	v_readlane_b32 s7, v243, 3
	s_waitcnt vmcnt(0)
	v_add_u32_e32 v16, v16, v4
	s_nop 2
	global_load_dword v5, v129, s[6:7] sc1
	v_readlane_b32 s6, v243, 4
	v_readlane_b32 s7, v243, 5
	s_waitcnt vmcnt(0)
	v_add_u32_e32 v16, v16, v5
	s_nop 2
	global_load_dword v6, v129, s[6:7] sc1
	v_readlane_b32 s6, v243, 6
	v_readlane_b32 s7, v243, 7
	s_waitcnt vmcnt(0)
	v_add_u32_e32 v16, v16, v6
	s_nop 2
	global_load_dword v7, v129, s[6:7] sc1
	v_readlane_b32 s6, v243, 8
	v_readlane_b32 s7, v243, 9
	s_waitcnt vmcnt(0)
	v_add_u32_e32 v16, v16, v7
	s_nop 2
	global_load_dword v8, v129, s[6:7] sc1
	v_readlane_b32 s6, v243, 10
	v_readlane_b32 s7, v243, 11
	s_waitcnt vmcnt(0)
	v_add_u32_e32 v16, v16, v8
	s_nop 2
	global_load_dword v9, v129, s[6:7] sc1
	v_readlane_b32 s6, v243, 12
	v_readlane_b32 s7, v243, 13
	s_waitcnt vmcnt(0)
	v_add_u32_e32 v16, v16, v9
	s_nop 2
	global_load_dword v10, v129, s[6:7] sc1
	v_readlane_b32 s6, v243, 14
	v_readlane_b32 s7, v243, 15
	s_waitcnt vmcnt(0)
	v_add_u32_e32 v16, v16, v10
	s_nop 2
	global_load_dword v11, v129, s[6:7] sc1
	v_readlane_b32 s6, v243, 16
	v_readlane_b32 s7, v243, 17
	s_waitcnt vmcnt(0)
	v_add_u32_e32 v16, v16, v11
	s_nop 2
	global_load_dword v12, v129, s[6:7] sc1
	v_readlane_b32 s6, v243, 18
	v_readlane_b32 s7, v243, 19
	s_waitcnt vmcnt(0)
	v_add_u32_e32 v16, v16, v12
	s_nop 2
	global_load_dword v13, v129, s[6:7] sc1
	v_readlane_b32 s6, v243, 20
	v_readlane_b32 s7, v243, 21
	s_waitcnt vmcnt(0)
	v_add_u32_e32 v16, v16, v13
	s_nop 2
	global_load_dword v14, v129, s[6:7] sc1
	v_readlane_b32 s6, v243, 22
	v_readlane_b32 s7, v243, 23
	s_waitcnt vmcnt(0)
	v_add_u32_e32 v16, v16, v14
	s_nop 2
	global_load_dword v15, v129, s[6:7] sc1
	s_mov_b64 s[6:7], -1
	s_waitcnt vmcnt(0)
	v_add_u32_e32 v16, v16, v15
	v_cmp_eq_u32_e32 vcc, s73, v16
	s_cbranch_vccnz .LBB0_381
	s_and_b32 s6, s10, 0xff
	s_cmp_eq_u32 s6, 0
	s_mov_b64 s[6:7], -1
	s_mov_b64 s[20:21], -1
	s_cbranch_scc1 .LBB0_386
	s_and_b64 vcc, exec, s[20:21]
	s_cbranch_vccz .LBB0_381

.LBB0_400:
	s_and_b32 s14, s10, 0xff
	s_mov_b64 s[24:25], -1
	s_cmp_lg_u32 s14, 0
	s_mov_b64 s[30:31], -1
	s_cbranch_scc0 .LBB0_403
	s_and_b64 vcc, exec, s[30:31]
	s_cbranch_vccz .LBB0_399

; __device__ __forceinline__ unsigned xb_ld(unsigned* p)              { return __hip_atomic_load(p, __ATOMIC_RELAXED, __HIP_MEMORY_SCOPE_AGENT); }
; __device__ __forceinline__ void xcd_barrier_complete(unsigned* bar, unsigned x, unsigned& nloc, unsigned& nx) {
;     const unsigned G = gridDim.x * gridDim.y * gridDim.z;
;     unsigned sum, cnt, mine, sp = 0u;
;     for (;;) {
;         sum = 0u; cnt = 0u; mine = 0u;
; #pragma unroll
;         for (unsigned j = 0; j < 16; ++j) { const unsigned c = xb_ld(&bar[XB_XCNT(j)]); sum += c; cnt += (c > 0u) ? 1u : 0u; mine = (j == x) ? c : mine; }
;         if (sum == G) break;
;         __builtin_amdgcn_s_sleep(1);
;         if ((++sp & 255u) == 0u) { if (xb_ld(&bar[XB_TMO])) break; if (sp > XB_SPIN_CAP) { atomicAdd(&bar[XB_TMO], 1u); break; } }
;     }
;     nloc = mine > 0u ? mine : 1u; nx = cnt > 0u ? cnt : 1u;
; }
.LBB0_1273:
	v_readlane_b32 s4, v243, 0
	v_readlane_b32 s5, v243, 1
	global_load_dword v3, v129, s[82:83] sc1
	s_waitcnt lgkmcnt(0)
	global_load_dword v0, v129, s[46:47] sc1
	global_load_dword v1, v129, s[30:31] sc1
	global_load_dword v2, v129, s[34:35] sc1
	s_mov_b64 s[6:7], -1
	global_load_dword v4, v129, s[4:5] sc1
	v_readlane_b32 s4, v243, 2
	v_readlane_b32 s5, v243, 3
	s_waitcnt vmcnt(3)
	v_add_u32_e32 v16, v0, v3
	s_nop 2
	global_load_dword v5, v129, s[4:5] sc1
	v_readlane_b32 s4, v243, 4
	v_readlane_b32 s5, v243, 5
	s_waitcnt vmcnt(3)
	v_add_u32_e32 v16, v16, v1
	s_waitcnt vmcnt(2)
	v_add_u32_e32 v16, v16, v2
	s_waitcnt vmcnt(1)
	v_add_u32_e32 v16, v16, v4
	s_waitcnt vmcnt(0)
	v_add_u32_e32 v16, v16, v5
	global_load_dword v6, v129, s[4:5] sc1
	v_readlane_b32 s4, v243, 6
	v_readlane_b32 s5, v243, 7
	s_waitcnt vmcnt(0)
	v_add_u32_e32 v16, v16, v6
	s_nop 2
	global_load_dword v7, v129, s[4:5] sc1
	v_readlane_b32 s4, v243, 8
	v_readlane_b32 s5, v243, 9
	s_waitcnt vmcnt(0)
	v_add_u32_e32 v16, v16, v7
	s_nop 2
	global_load_dword v8, v129, s[4:5] sc1
	v_readlane_b32 s4, v243, 10
	v_readlane_b32 s5, v243, 11
	s_waitcnt vmcnt(0)
	v_add_u32_e32 v16, v16, v8
	s_nop 2
	global_load_dword v9, v129, s[4:5] sc1
	v_readlane_b32 s4, v243, 12
	v_readlane_b32 s5, v243, 13
	s_waitcnt vmcnt(0)
	v_add_u32_e32 v16, v16, v9
	s_nop 2
	global_load_dword v10, v129, s[4:5] sc1
	v_readlane_b32 s4, v243, 14
	v_readlane_b32 s5, v243, 15
	s_waitcnt vmcnt(0)
	v_add_u32_e32 v16, v16, v10
	s_nop 2
	global_load_dword v11, v129, s[4:5] sc1
	v_readlane_b32 s4, v243, 16
	v_readlane_b32 s5, v243, 17
	s_waitcnt vmcnt(0)
	v_add_u32_e32 v16, v16, v11
	s_nop 2
	global_load_dword v12, v129, s[4:5] sc1
	v_readlane_b32 s4, v243, 18
	v_readlane_b32 s5, v243, 19
	s_waitcnt vmcnt(0)
	v_add_u32_e32 v16, v16, v12
	s_nop 2
	global_load_dword v13, v129, s[4:5] sc1
	v_readlane_b32 s4, v243, 20
	v_readlane_b32 s5, v243, 21
	s_waitcnt vmcnt(0)
	v_add_u32_e32 v16, v16, v13
	s_nop 2
	global_load_dword v14, v129, s[4:5] sc1
	v_readlane_b32 s4, v243, 22
	v_readlane_b32 s5, v243, 23
	s_waitcnt vmcnt(0)
	v_add_u32_e32 v16, v16, v14
	s_nop 2
	global_load_dword v15, v129, s[4:5] sc1
	s_mov_b64 s[4:5], -1
	s_waitcnt vmcnt(0)
	v_add_u32_e32 v16, v16, v15
	v_cmp_eq_u32_e32 vcc, s73, v16
	s_cbranch_vccnz .LBB0_1272
	s_and_b32 s4, s10, 0xff
	s_cmp_eq_u32 s4, 0
	s_mov_b64 s[4:5], -1
	s_mov_b64 s[12:13], -1
	s_cbranch_scc1 .LBB0_1277
	s_and_b64 vcc, exec, s[12:13]
	s_cbranch_vccz .LBB0_1272

; __device__ __forceinline__ unsigned xb_ld(unsigned* p)              { return __hip_atomic_load(p, __ATOMIC_RELAXED, __HIP_MEMORY_SCOPE_AGENT); }
; __device__ __forceinline__ void xcd_barrier_complete(unsigned* bar, unsigned x, unsigned& nloc, unsigned& nx) {
;     const unsigned G = gridDim.x * gridDim.y * gridDim.z;
;     unsigned sum, cnt, mine, sp = 0u;
;     for (;;) {
;         sum = 0u; cnt = 0u; mine = 0u;
; #pragma unroll
;         for (unsigned j = 0; j < 16; ++j) { const unsigned c = xb_ld(&bar[XB_XCNT(j)]); sum += c; cnt += (c > 0u) ? 1u : 0u; mine = (j == x) ? c : mine; }
;         if (sum == G) break;
;         __builtin_amdgcn_s_sleep(1);
;         if ((++sp & 255u) == 0u) { if (xb_ld(&bar[XB_TMO])) break; if (sp > XB_SPIN_CAP) { atomicAdd(&bar[XB_TMO], 1u); break; } }
;     }
;     nloc = mine > 0u ? mine : 1u; nx = cnt > 0u ? cnt : 1u;
; }
.LBB0_1357:
	v_readlane_b32 s12, v242, 31
	v_readlane_b32 s13, v242, 32
	global_load_dword v1, v129, s[82:83] sc1
	s_waitcnt lgkmcnt(0)
	global_load_dword v0, v129, s[46:47] sc1
	s_mov_b64 s[20:21], -1
	s_waitcnt vmcnt(0)
	v_add_u32_e32 v16, v0, v1
	global_load_dword v2, v129, s[12:13] sc1
	v_readlane_b32 s12, v242, 33
	v_readlane_b32 s13, v242, 34
	s_waitcnt vmcnt(0)
	v_add_u32_e32 v16, v16, v2
	s_nop 2
	global_load_dword v3, v129, s[12:13] sc1
	v_readlane_b32 s12, v243, 0
	v_readlane_b32 s13, v243, 1
	s_waitcnt vmcnt(0)
	v_add_u32_e32 v16, v16, v3
	s_nop 2
	global_load_dword v4, v129, s[12:13] sc1
	v_readlane_b32 s12, v243, 2
	v_readlane_b32 s13, v243, 3
	s_waitcnt vmcnt(0)
	v_add_u32_e32 v16, v16, v4
	s_nop 2
	global_load_dword v5, v129, s[12:13] sc1
	v_readlane_b32 s12, v243, 4
	v_readlane_b32 s13, v243, 5
	s_waitcnt vmcnt(0)
	v_add_u32_e32 v16, v16, v5
	s_nop 2
	global_load_dword v6, v129, s[12:13] sc1
	v_readlane_b32 s12, v243, 6
	v_readlane_b32 s13, v243, 7
	s_waitcnt vmcnt(0)
	v_add_u32_e32 v16, v16, v6
	s_nop 2
	global_load_dword v7, v129, s[12:13] sc1
	v_readlane_b32 s12, v243, 8
	v_readlane_b32 s13, v243, 9
	s_waitcnt vmcnt(0)
	v_add_u32_e32 v16, v16, v7
	s_nop 2
	global_load_dword v8, v129, s[12:13] sc1
	v_readlane_b32 s12, v243, 10
	v_readlane_b32 s13, v243, 11
	s_waitcnt vmcnt(0)
	v_add_u32_e32 v16, v16, v8
	s_nop 2
	global_load_dword v9, v129, s[12:13] sc1
	v_readlane_b32 s12, v243, 12
	v_readlane_b32 s13, v243, 13
	s_waitcnt vmcnt(0)
	v_add_u32_e32 v16, v16, v9
	s_nop 2
	global_load_dword v10, v129, s[12:13] sc1
	v_readlane_b32 s12, v243, 14
	v_readlane_b32 s13, v243, 15
	s_waitcnt vmcnt(0)
	v_add_u32_e32 v16, v16, v10
	s_nop 2
	global_load_dword v11, v129, s[12:13] sc1
	v_readlane_b32 s12, v243, 16
	v_readlane_b32 s13, v243, 17
	s_waitcnt vmcnt(0)
	v_add_u32_e32 v16, v16, v11
	s_nop 2
	global_load_dword v12, v129, s[12:13] sc1
	v_readlane_b32 s12, v243, 18
	v_readlane_b32 s13, v243, 19
	s_waitcnt vmcnt(0)
	v_add_u32_e32 v16, v16, v12
	s_nop 2
	global_load_dword v13, v129, s[12:13] sc1
	v_readlane_b32 s12, v243, 20
	v_readlane_b32 s13, v243, 21
	s_waitcnt vmcnt(0)
	v_add_u32_e32 v16, v16, v13
	s_nop 2
	global_load_dword v14, v129, s[12:13] sc1
	v_readlane_b32 s12, v243, 22
	v_readlane_b32 s13, v243, 23
	s_waitcnt vmcnt(0)
	v_add_u32_e32 v16, v16, v14
	s_nop 2
	global_load_dword v15, v129, s[12:13] sc1
	s_mov_b64 s[12:13], -1
	s_waitcnt vmcnt(0)
	v_add_u32_e32 v16, v16, v15
	v_cmp_eq_u32_e32 vcc, s73, v16
	s_cbranch_vccnz .LBB0_1356
	s_and_b32 s12, s10, 0xff
	s_cmp_eq_u32 s12, 0
	s_mov_b64 s[12:13], -1
	s_mov_b64 s[22:23], -1
	s_cbranch_scc1 .LBB0_1361
	s_and_b64 vcc, exec, s[22:23]
	s_cbranch_vccz .LBB0_1356

.LBB0_1378:
	s_and_b32 s14, s10, 0xff
	s_mov_b64 s[26:27], -1
	s_cmp_lg_u32 s14, 0
	s_mov_b64 s[36:37], -1
	s_cbranch_scc0 .LBB0_1381
	s_and_b64 vcc, exec, s[36:37]
	s_cbranch_vccz .LBB0_1377
